# in-proj GEMM: whole-tile fast epilogues for plain (bx) and product (cx*xx) tiles
# baseline (speedup 1.0000x reference)
.LBB0_168:
	s_cmp_gt_u32 s6, 14
	s_cbranch_scc1 .Lp2_sig
	s_cmp_lt_u32 s6, 12
	s_cbranch_scc1 .Lp2_lo
	s_lshl_b32 s65, s4, 8
	s_cmp_gt_i32 s6, 3
	s_cselect_b64 s[94:95], -1, 0
	v_readlane_b32 s66, v250, 46
	v_add_u32_e32 v148, s65, v139
	s_mov_b64 s[4:5], -1
	s_and_b64 vcc, exec, s[94:95]
	v_readlane_b32 s67, v250, 47
	s_cbranch_vccz .LBB0_196
	s_cmp_gt_u32 s6, 11
	s_cbranch_scc0 .LBB0_191
	s_cmp_gt_u32 s6, 14
	s_cbranch_scc0 .LBB0_174
	v_cmp_gt_i32_e32 vcc, s80, v148
	s_and_saveexec_b64 s[4:5], vcc
	s_cbranch_execz .LBB0_173
	s_cmp_gt_u32 s6, 18
	s_cselect_b64 s[12:13], -1, 0
	s_and_b64 s[52:53], s[12:13], exec
	s_cselect_b32 s3, 0xffffffed, -15
	s_add_i32 s3, s3, s6
	s_and_b64 s[52:53], s[12:13], exec
	v_readlane_b32 s36, v250, 22
	v_lshl_or_b32 v136, s3, 8, v138
	s_cselect_b32 s3, 0x1000, 0
	v_readlane_b32 s38, v250, 24
	v_readlane_b32 s39, v250, 25
	s_add_u32 s52, s38, s3
	s_addc_u32 s53, s39, 0
	v_lshl_add_u64 v[174:175], v[136:137], 2, s[52:53]
	global_load_dwordx4 v[162:165], v[174:175], off
	global_load_dwordx4 v[166:169], v[174:175], off offset:16
	global_load_dwordx4 v[170:173], v[174:175], off offset:512
	s_nop 0
	global_load_dwordx4 v[174:177], v[174:175], off offset:528
	v_ashrrev_i32_e32 v149, 31, v148
	v_lshlrev_b64 v[178:179], 11, v[148:149]
	v_readlane_b32 s44, v250, 30
	v_readlane_b32 s45, v250, 31
	v_readlane_b32 s44, v250, 52
	v_readlane_b32 s45, v250, 53
	s_and_b64 s[12:13], s[12:13], exec
	v_readlane_b32 s42, v250, 28
	v_readlane_b32 s43, v250, 29
	s_cselect_b32 s13, s45, s31
	s_cselect_b32 s12, s44, s30
	v_readlane_b32 s42, v250, 50
	v_readlane_b32 s38, v250, 38
	v_lshl_add_u64 v[178:179], s[12:13], 0, v[178:179]
	v_readlane_b32 s43, v250, 51
	v_readlane_b32 s39, v250, 39
	v_readlane_b32 s37, v250, 23
	v_readlane_b32 s40, v250, 26
	v_readlane_b32 s41, v250, 27
	v_readlane_b32 s46, v250, 32
	v_readlane_b32 s47, v250, 33
	v_readlane_b32 s48, v250, 34
	v_readlane_b32 s49, v250, 35
	v_readlane_b32 s50, v250, 36
	v_readlane_b32 s51, v250, 37
	s_waitcnt vmcnt(0)
	v_add_f32_e32 v149, v124, v162
	v_add_f32_e32 v161, v120, v166
	v_add_f32_e32 v162, v116, v170
	v_add_f32_e32 v166, v112, v174
	v_add_f32_e32 v163, v125, v163
	v_add_f32_e32 v164, v126, v164
	v_add_f32_e32 v165, v127, v165
	v_add_f32_e32 v169, v123, v169
	v_add_f32_e32 v167, v121, v167
	v_add_f32_e32 v170, v117, v171
	v_add_f32_e32 v171, v113, v175
	v_add_f32_e32 v168, v122, v168
	v_add_f32_e32 v173, v119, v173
	v_add_f32_e32 v175, v115, v177
	v_mul_f32_e32 v162, 0xbfb8aa3b, v162
	v_mul_f32_e32 v166, 0xbfb8aa3b, v166
	v_mul_f32_e32 v163, 0xbfb8aa3b, v163
	v_mul_f32_e32 v164, 0xbfb8aa3b, v164
	v_mul_f32_e32 v165, 0xbfb8aa3b, v165
	v_mul_f32_e32 v169, 0xbfb8aa3b, v169
	v_add_f32_e32 v172, v118, v172
	v_add_f32_e32 v174, v114, v176
	v_mul_f32_e32 v149, 0xbfb8aa3b, v149
	v_mul_f32_e32 v161, 0xbfb8aa3b, v161
	v_mul_f32_e32 v167, 0xbfb8aa3b, v167
	v_mul_f32_e32 v168, 0xbfb8aa3b, v168
	v_mul_f32_e32 v173, 0xbfb8aa3b, v173
	v_mul_f32_e32 v175, 0xbfb8aa3b, v175
	v_exp_f32_e32 v162, v162
	v_exp_f32_e32 v166, v166
	v_exp_f32_e32 v163, v163
	v_exp_f32_e32 v164, v164
	v_exp_f32_e32 v165, v165
	v_exp_f32_e32 v169, v169
	v_mul_f32_e32 v170, 0xbfb8aa3b, v170
	v_mul_f32_e32 v171, 0xbfb8aa3b, v171
	v_mul_f32_e32 v172, 0xbfb8aa3b, v172
	v_mul_f32_e32 v174, 0xbfb8aa3b, v174
	v_exp_f32_e32 v149, v149
	v_exp_f32_e32 v161, v161
	v_exp_f32_e32 v167, v167
	v_exp_f32_e32 v168, v168
	v_exp_f32_e32 v173, v173
	v_exp_f32_e32 v175, v175
	v_exp_f32_e32 v170, v170
	v_exp_f32_e32 v171, v171
	v_exp_f32_e32 v172, v172
	v_exp_f32_e32 v174, v174
	v_add_f32_e32 v162, 1.0, v162
	v_add_f32_e32 v166, 1.0, v166
	v_add_f32_e32 v163, 1.0, v163
	v_add_f32_e32 v164, 1.0, v164
	v_add_f32_e32 v165, 1.0, v165
	v_add_f32_e32 v169, 1.0, v169
	v_add_f32_e32 v149, 1.0, v149
	v_add_f32_e32 v161, 1.0, v161
	v_add_f32_e32 v167, 1.0, v167
	v_add_f32_e32 v168, 1.0, v168
	v_add_f32_e32 v173, 1.0, v173
	v_rcp_f32_e32 v176, v162
	v_rcp_f32_e32 v177, v166
	v_rcp_f32_e32 v162, v163
	v_rcp_f32_e32 v163, v164
	v_rcp_f32_e32 v164, v165
	v_rcp_f32_e32 v165, v169
	v_add_f32_e32 v166, 1.0, v175
	v_add_f32_e32 v170, 1.0, v170
	v_add_f32_e32 v171, 1.0, v171
	v_add_f32_e32 v172, 1.0, v172
	v_add_f32_e32 v174, 1.0, v174
	v_rcp_f32_e32 v149, v149
	v_rcp_f32_e32 v161, v161
	v_rcp_f32_e32 v180, v167
	v_rcp_f32_e32 v168, v168
	v_rcp_f32_e32 v169, v173
	v_rcp_f32_e32 v173, v166
	v_lshl_add_u64 v[166:167], v[136:137], 1, v[178:179]
	v_cvt_pk_bf16_f32 v162, v149, v162
	v_cvt_pk_bf16_f32 v163, v163, v164
	v_cvt_pk_bf16_f32 v164, v161, v180
	v_cvt_pk_bf16_f32 v165, v168, v165
	v_rcp_f32_e32 v170, v170
	v_rcp_f32_e32 v171, v171
	v_rcp_f32_e32 v172, v172
	v_rcp_f32_e32 v174, v174
	global_store_dwordx4 v[166:167], v[162:165], off
	s_nop 1
	v_cvt_pk_bf16_f32 v162, v176, v170
	v_cvt_pk_bf16_f32 v163, v172, v169
	v_cvt_pk_bf16_f32 v164, v177, v171
	v_cvt_pk_bf16_f32 v165, v174, v173
	global_store_dwordx4 v[166:167], v[162:165], off offset:256

.Lp2_lo:
	s_cmp_gt_u32 s4, 63
	s_cbranch_scc1 .LBB0_396
	s_lshl_b32 s65, s4, 8
	v_add_u32_e32 v148, s65, v139
	v_ashrrev_i32_e32 v149, 31, v148
	v_lshlrev_b64 v[148:149], 11, v[148:149]
	v_lshlrev_b32_e32 v136, 1, v138
	s_mov_b32 s98, 0x8000
	s_mov_b32 s99, 0
	s_mov_b32 s100, 0x28000
	s_mov_b32 s101, 0
	s_cmp_lt_u32 s6, 4
	s_cbranch_scc0 .Lp2_uu
	s_lshl_b32 s40, s6, 9
	s_mov_b32 s41, 0
	v_lshl_add_u64 v[148:149], s[42:43], 0, v[148:149]
	v_lshl_add_u64 v[148:149], s[40:41], 0, v[148:149]
	v_lshl_add_u64 v[148:149], v[136:137], 0, v[148:149]
	v_cvt_pk_bf16_f32 v124, v124, v125
	v_cvt_pk_bf16_f32 v125, v126, v127
	v_cvt_pk_bf16_f32 v126, v120, v121
	v_cvt_pk_bf16_f32 v127, v122, v123
	global_store_dwordx4 v[148:149], v[124:127], off
	v_cvt_pk_bf16_f32 v116, v116, v117
	v_cvt_pk_bf16_f32 v117, v118, v119
	v_cvt_pk_bf16_f32 v118, v112, v113
	v_cvt_pk_bf16_f32 v119, v114, v115
	global_store_dwordx4 v[148:149], v[116:119], off offset:256
	v_lshl_add_u64 v[148:149], v[148:149], 0, s[98:99]
	v_cvt_pk_bf16_f32 v108, v108, v109
	v_cvt_pk_bf16_f32 v109, v110, v111
	v_cvt_pk_bf16_f32 v110, v104, v105
	v_cvt_pk_bf16_f32 v111, v106, v107
	global_store_dwordx4 v[148:149], v[108:111], off
	v_cvt_pk_bf16_f32 v100, v100, v101
	v_cvt_pk_bf16_f32 v101, v102, v103
	v_cvt_pk_bf16_f32 v102, v96, v97
	v_cvt_pk_bf16_f32 v103, v98, v99
	global_store_dwordx4 v[148:149], v[100:103], off offset:256
	v_lshl_add_u64 v[148:149], v[148:149], 0, s[98:99]
	v_cvt_pk_bf16_f32 v92, v92, v93
	v_cvt_pk_bf16_f32 v93, v94, v95
	v_cvt_pk_bf16_f32 v94, v88, v89
	v_cvt_pk_bf16_f32 v95, v90, v91
	global_store_dwordx4 v[148:149], v[92:95], off
	v_cvt_pk_bf16_f32 v84, v84, v85
	v_cvt_pk_bf16_f32 v85, v86, v87
	v_cvt_pk_bf16_f32 v86, v80, v81
	v_cvt_pk_bf16_f32 v87, v82, v83
	global_store_dwordx4 v[148:149], v[84:87], off offset:256
	v_lshl_add_u64 v[148:149], v[148:149], 0, s[98:99]
	v_cvt_pk_bf16_f32 v76, v76, v77
	v_cvt_pk_bf16_f32 v77, v78, v79
	v_cvt_pk_bf16_f32 v78, v72, v73
	v_cvt_pk_bf16_f32 v79, v74, v75
	global_store_dwordx4 v[148:149], v[76:79], off
	v_cvt_pk_bf16_f32 v68, v68, v69
	v_cvt_pk_bf16_f32 v69, v70, v71
	v_cvt_pk_bf16_f32 v70, v64, v65
	v_cvt_pk_bf16_f32 v71, v66, v67
	global_store_dwordx4 v[148:149], v[68:71], off offset:256
	v_lshl_add_u64 v[148:149], v[148:149], 0, s[100:101]
	v_cvt_pk_bf16_f32 v60, v60, v61
	v_cvt_pk_bf16_f32 v61, v62, v63
	v_cvt_pk_bf16_f32 v62, v56, v57
	v_cvt_pk_bf16_f32 v63, v58, v59
	global_store_dwordx4 v[148:149], v[60:63], off
	v_cvt_pk_bf16_f32 v52, v52, v53
	v_cvt_pk_bf16_f32 v53, v54, v55
	v_cvt_pk_bf16_f32 v54, v48, v49
	v_cvt_pk_bf16_f32 v55, v50, v51
	global_store_dwordx4 v[148:149], v[52:55], off offset:256
	v_lshl_add_u64 v[148:149], v[148:149], 0, s[98:99]
	v_cvt_pk_bf16_f32 v44, v44, v45
	v_cvt_pk_bf16_f32 v45, v46, v47
	v_cvt_pk_bf16_f32 v46, v40, v41
	v_cvt_pk_bf16_f32 v47, v42, v43
	global_store_dwordx4 v[148:149], v[44:47], off
	v_cvt_pk_bf16_f32 v36, v36, v37
	v_cvt_pk_bf16_f32 v37, v38, v39
	v_cvt_pk_bf16_f32 v38, v32, v33
	v_cvt_pk_bf16_f32 v39, v34, v35
	global_store_dwordx4 v[148:149], v[36:39], off offset:256
	v_lshl_add_u64 v[148:149], v[148:149], 0, s[98:99]
	v_cvt_pk_bf16_f32 v28, v28, v29
	v_cvt_pk_bf16_f32 v29, v30, v31
	v_cvt_pk_bf16_f32 v30, v24, v25
	v_cvt_pk_bf16_f32 v31, v26, v27
	global_store_dwordx4 v[148:149], v[28:31], off
	v_cvt_pk_bf16_f32 v20, v20, v21
	v_cvt_pk_bf16_f32 v21, v22, v23
	v_cvt_pk_bf16_f32 v22, v16, v17
	v_cvt_pk_bf16_f32 v23, v18, v19
	global_store_dwordx4 v[148:149], v[20:23], off offset:256
	v_lshl_add_u64 v[148:149], v[148:149], 0, s[98:99]
	v_cvt_pk_bf16_f32 v12, v12, v13
	v_cvt_pk_bf16_f32 v13, v14, v15
	v_cvt_pk_bf16_f32 v14, v8, v9
	v_cvt_pk_bf16_f32 v15, v10, v11
	global_store_dwordx4 v[148:149], v[12:15], off
	v_cvt_pk_bf16_f32 v4, v4, v5
	v_cvt_pk_bf16_f32 v5, v6, v7
	v_cvt_pk_bf16_f32 v6, v0, v1
	v_cvt_pk_bf16_f32 v7, v2, v3
	global_store_dwordx4 v[148:149], v[4:7], off offset:256
	s_branch .LBB0_396
.Lp2_uu:
	v_readlane_b32 s36, v250, 46
	v_readlane_b32 s37, v250, 47
	s_add_i32 s40, s6, -4
	s_lshl_b32 s40, s40, 8
	s_mov_b32 s41, 0
	v_lshl_add_u64 v[148:149], s[36:37], 0, v[148:149]
	v_lshl_add_u64 v[148:149], s[40:41], 0, v[148:149]
	v_lshl_add_u64 v[148:149], v[136:137], 0, v[148:149]
	v_mul_f32_e32 v124, v124, v116
	v_mul_f32_e32 v125, v125, v117
	v_mul_f32_e32 v126, v126, v118
	v_mul_f32_e32 v127, v127, v119
	v_mul_f32_e32 v120, v120, v112
	v_mul_f32_e32 v121, v121, v113
	v_mul_f32_e32 v122, v122, v114
	v_mul_f32_e32 v123, v123, v115
	v_cvt_pk_bf16_f32 v124, v124, v125
	v_cvt_pk_bf16_f32 v125, v126, v127
	v_cvt_pk_bf16_f32 v126, v120, v121
	v_cvt_pk_bf16_f32 v127, v122, v123
	global_store_dwordx4 v[148:149], v[124:127], off
	v_lshl_add_u64 v[148:149], v[148:149], 0, s[98:99]
	v_mul_f32_e32 v108, v108, v100
	v_mul_f32_e32 v109, v109, v101
	v_mul_f32_e32 v110, v110, v102
	v_mul_f32_e32 v111, v111, v103
	v_mul_f32_e32 v104, v104, v96
	v_mul_f32_e32 v105, v105, v97
	v_mul_f32_e32 v106, v106, v98
	v_mul_f32_e32 v107, v107, v99
	v_cvt_pk_bf16_f32 v108, v108, v109
	v_cvt_pk_bf16_f32 v109, v110, v111
	v_cvt_pk_bf16_f32 v110, v104, v105
	v_cvt_pk_bf16_f32 v111, v106, v107
	global_store_dwordx4 v[148:149], v[108:111], off
	v_lshl_add_u64 v[148:149], v[148:149], 0, s[98:99]
	v_mul_f32_e32 v92, v92, v84
	v_mul_f32_e32 v93, v93, v85
	v_mul_f32_e32 v94, v94, v86
	v_mul_f32_e32 v95, v95, v87
	v_mul_f32_e32 v88, v88, v80
	v_mul_f32_e32 v89, v89, v81
	v_mul_f32_e32 v90, v90, v82
	v_mul_f32_e32 v91, v91, v83
	v_cvt_pk_bf16_f32 v92, v92, v93
	v_cvt_pk_bf16_f32 v93, v94, v95
	v_cvt_pk_bf16_f32 v94, v88, v89
	v_cvt_pk_bf16_f32 v95, v90, v91
	global_store_dwordx4 v[148:149], v[92:95], off
	v_lshl_add_u64 v[148:149], v[148:149], 0, s[98:99]
	v_mul_f32_e32 v76, v76, v68
	v_mul_f32_e32 v77, v77, v69
	v_mul_f32_e32 v78, v78, v70
	v_mul_f32_e32 v79, v79, v71
	v_mul_f32_e32 v72, v72, v64
	v_mul_f32_e32 v73, v73, v65
	v_mul_f32_e32 v74, v74, v66
	v_mul_f32_e32 v75, v75, v67
	v_cvt_pk_bf16_f32 v76, v76, v77
	v_cvt_pk_bf16_f32 v77, v78, v79
	v_cvt_pk_bf16_f32 v78, v72, v73
	v_cvt_pk_bf16_f32 v79, v74, v75
	global_store_dwordx4 v[148:149], v[76:79], off
	v_lshl_add_u64 v[148:149], v[148:149], 0, s[100:101]
	v_mul_f32_e32 v60, v60, v52
	v_mul_f32_e32 v61, v61, v53
	v_mul_f32_e32 v62, v62, v54
	v_mul_f32_e32 v63, v63, v55
	v_mul_f32_e32 v56, v56, v48
	v_mul_f32_e32 v57, v57, v49
	v_mul_f32_e32 v58, v58, v50
	v_mul_f32_e32 v59, v59, v51
	v_cvt_pk_bf16_f32 v60, v60, v61
	v_cvt_pk_bf16_f32 v61, v62, v63
	v_cvt_pk_bf16_f32 v62, v56, v57
	v_cvt_pk_bf16_f32 v63, v58, v59
	global_store_dwordx4 v[148:149], v[60:63], off
	v_lshl_add_u64 v[148:149], v[148:149], 0, s[98:99]
	v_mul_f32_e32 v44, v44, v36
	v_mul_f32_e32 v45, v45, v37
	v_mul_f32_e32 v46, v46, v38
	v_mul_f32_e32 v47, v47, v39
	v_mul_f32_e32 v40, v40, v32
	v_mul_f32_e32 v41, v41, v33
	v_mul_f32_e32 v42, v42, v34
	v_mul_f32_e32 v43, v43, v35
	v_cvt_pk_bf16_f32 v44, v44, v45
	v_cvt_pk_bf16_f32 v45, v46, v47
	v_cvt_pk_bf16_f32 v46, v40, v41
	v_cvt_pk_bf16_f32 v47, v42, v43
	global_store_dwordx4 v[148:149], v[44:47], off
	v_lshl_add_u64 v[148:149], v[148:149], 0, s[98:99]
	v_mul_f32_e32 v28, v28, v20
	v_mul_f32_e32 v29, v29, v21
	v_mul_f32_e32 v30, v30, v22
	v_mul_f32_e32 v31, v31, v23
	v_mul_f32_e32 v24, v24, v16
	v_mul_f32_e32 v25, v25, v17
	v_mul_f32_e32 v26, v26, v18
	v_mul_f32_e32 v27, v27, v19
	v_cvt_pk_bf16_f32 v28, v28, v29
	v_cvt_pk_bf16_f32 v29, v30, v31
	v_cvt_pk_bf16_f32 v30, v24, v25
	v_cvt_pk_bf16_f32 v31, v26, v27
	global_store_dwordx4 v[148:149], v[28:31], off
	v_lshl_add_u64 v[148:149], v[148:149], 0, s[98:99]
	v_mul_f32_e32 v12, v12, v4
	v_mul_f32_e32 v13, v13, v5
	v_mul_f32_e32 v14, v14, v6
	v_mul_f32_e32 v15, v15, v7
	v_mul_f32_e32 v8, v8, v0
	v_mul_f32_e32 v9, v9, v1
	v_mul_f32_e32 v10, v10, v2
	v_mul_f32_e32 v11, v11, v3
	v_cvt_pk_bf16_f32 v12, v12, v13
	v_cvt_pk_bf16_f32 v13, v14, v15
	v_cvt_pk_bf16_f32 v14, v8, v9
	v_cvt_pk_bf16_f32 v15, v10, v11
	global_store_dwordx4 v[148:149], v[12:15], off
	s_branch .LBB0_396
